# PLE sample rows as 256 skinny units (gate chain on waves 0-3 -> sigmoid -> bf16 via LDS, proj chain on waves 4-7, f32 into slab 0) instead of 8 full tiles on 8 blocks
# speedup vs baseline: 1.0073x; 1.0033x over previous
;     DI void init(int ntm_, int ntn_, int bid, int nb) {
;         ntm = ntm_; ntn = ntn_;
;         const int nt = ntm * ntn;
;         if ((nb & 7) == 0) { const int x = bid & 7, per = (nt + 7) >> 3; L = x * per + (bid >> 3); end = min((x + 1) * per, nt); step = nb >> 3; }
;         else { L = bid; end = nt; step = nb; }
;     }
; DI void gemm_ple(const Params& p, int bid, int nb, char* smem, const int tid) {
;     ...
;     const int ntn = 8, ntiles = 130 * ntn;
;     TileIter ti; ti.init(65, ntn, bid, nb);
.LBB0_109:
	s_mov_b64 s[70:71], s[46:47]
	s_andn2_b64 vcc, exec, s[0:1]
	s_cbranch_vccnz .LBB0_147
	v_readlane_b32 s0, v240, 53
	v_readlane_b32 s1, v240, 54
	s_andn2_b64 vcc, exec, s[0:1]
	v_readlane_b32 s0, v231, 0
	v_readlane_b32 s1, v231, 1
	s_mov_b32 s11, s0
	v_readlane_b32 s0, v238, 54
	s_movk_i32 s10, 0x200
	s_mov_b32 s33, s0
	v_readlane_b32 s1, v238, 55
	s_cbranch_vccz .LBB0_113
	s_cmp_lt_i32 s11, s10
	s_cselect_b64 s[0:1], -1, 0
	s_cmp_ge_i32 s11, s10
	s_cbranch_scc1 .LBB0_114

;     DI void init(int ntm_, int ntn_, int bid, int nb) {
;         ntm = ntm_; ntn = ntn_;
;         const int nt = ntm * ntn;
;         if ((nb & 7) == 0) { const int x = bid & 7, per = (nt + 7) >> 3; L = x * per + (bid >> 3); end = min((x + 1) * per, nt); step = nb >> 3; }
;         else { L = bid; end = nt; step = nb; }
;     }
.LBB0_113:
	v_readlane_b32 s0, v231, 0
	v_readlane_b32 s1, v231, 1
	s_mov_b32 s2, s0
	s_and_b32 s0, s0, 7
	s_mulk_i32 s0, 0x40
	s_ashr_i32 s1, s2, 3
	s_add_i32 s11, s0, s1
	s_add_i32 s10, s0, 0x40
	v_readlane_b32 s33, v240, 55
	s_cmp_lt_i32 s11, s10
	s_cselect_b64 s[0:1], -1, 0
	s_cmp_ge_i32 s11, s10
	s_cbranch_scc0 .LBB0_112

; DI unsigned pk2(float lo, float hi) { const f32x2 v = {lo, hi}; return __builtin_bit_cast(unsigned, __builtin_convertvector(v, bf2_t)); }
; DI void gemm_ple(const Params& p, int bid, int nb, char* smem, const int tid) {
;     ...
;         u32x2 gpk[4][4];
;         {
;             f32x4 gate[4][4]; zero_acc(gate);
;             gemm_stream2(XN, 1024, WG, 1024, 1024, m0, n0, true, PB, 256, WP, 256, m0, n0, smem, gate, tid, rg);
; #pragma unroll
;             for (int i = 0; i < 4; ++i)
; #pragma unroll
;                 for (int j = 0; j < 4; ++j) {
;                     float g[4];
; #pragma unroll
;                     for (int e = 0; e < 4; ++e) g[e] = __builtin_amdgcn_rcpf(1.0f + __builtin_amdgcn_exp2f(-LOG2E * gate[i][j][e]));
;                     gpk[i][j].x = pk2(g[0], g[1]); gpk[i][j].y = pk2(g[2], g[3]);
;                 }
;         }
.Lple_done:
	s_mov_b64 s[46:47], s[70:71]
.Lpss_entry:
	s_waitcnt vmcnt(0) lgkmcnt(0)
	s_barrier
	v_readlane_b32 s55, v240, 0
	v_readlane_b32 s53, v238, 54
	v_readfirstlane_b32 s10, v193
	s_nop 3
	s_lshr_b32 s10, s10, 6
	s_cmpk_lt_u32 s55, 0x100
	s_cbranch_scc0 .Lple_exit
	v_and_b32_e32 v190, 63, v193
	v_and_b32_e32 v191, 15, v190
	v_lshrrev_b32_e32 v17, 4, v190
	v_lshlrev_b32_e32 v189, 4, v17
	s_and_b32 s3, s10, 3
	s_lshl_b32 s3, s3, 9
	v_lshl_add_u32 v187, v190, 3, s3
	v_add_u32_e32 v187, 16, v187
.Lpss_u:
	s_lshr_b32 s93, s55, 4
	s_and_b32 s98, s55, 15
	s_and_b32 s3, s10, 3
	s_lshl_b32 s3, s3, 4
	s_lshl_b32 s2, s98, 6
	s_add_u32 s3, s3, s2
	s_cmp_ge_u32 s10, 4
	s_cbranch_scc1 .Lpss_proj
	v_lshl_add_u32 v186, v191, 11, v189
	s_lshl_b32 s1, s93, 15
	s_add_u32 s1, s1, 0x5240000
	s_add_u32 s66, s88, s1
	s_addc_u32 s67, s89, 0
	s_lshl_b32 s1, s3, 11
	s_add_u32 s1, s1, 0x27a0000
	s_add_u32 s70, s88, s1
	s_addc_u32 s71, s89, 0
	global_load_dwordx4 v[28:31], v186, s[66:67] offset:0
	global_load_dwordx4 v[92:95], v186, s[70:71] offset:0
	global_load_dwordx4 v[32:35], v186, s[66:67] offset:64
	global_load_dwordx4 v[96:99], v186, s[70:71] offset:64
	global_load_dwordx4 v[36:39], v186, s[66:67] offset:128
	global_load_dwordx4 v[100:103], v186, s[70:71] offset:128
	global_load_dwordx4 v[40:43], v186, s[66:67] offset:192
	global_load_dwordx4 v[104:107], v186, s[70:71] offset:192
	global_load_dwordx4 v[44:47], v186, s[66:67] offset:256
	global_load_dwordx4 v[108:111], v186, s[70:71] offset:256
	global_load_dwordx4 v[48:51], v186, s[66:67] offset:320
	global_load_dwordx4 v[112:115], v186, s[70:71] offset:320
	global_load_dwordx4 v[52:55], v186, s[66:67] offset:384
	global_load_dwordx4 v[116:119], v186, s[70:71] offset:384
	global_load_dwordx4 v[56:59], v186, s[66:67] offset:448
	global_load_dwordx4 v[120:123], v186, s[70:71] offset:448
	global_load_dwordx4 v[60:63], v186, s[66:67] offset:512
	global_load_dwordx4 v[124:127], v186, s[70:71] offset:512
	global_load_dwordx4 v[64:67], v186, s[66:67] offset:576
	global_load_dwordx4 v[128:131], v186, s[70:71] offset:576
	global_load_dwordx4 v[68:71], v186, s[66:67] offset:640
	global_load_dwordx4 v[132:135], v186, s[70:71] offset:640
	global_load_dwordx4 v[72:75], v186, s[66:67] offset:704
	global_load_dwordx4 v[136:139], v186, s[70:71] offset:704
	global_load_dwordx4 v[76:79], v186, s[66:67] offset:768
	global_load_dwordx4 v[140:143], v186, s[70:71] offset:768
	global_load_dwordx4 v[80:83], v186, s[66:67] offset:832
	global_load_dwordx4 v[144:147], v186, s[70:71] offset:832
	global_load_dwordx4 v[84:87], v186, s[66:67] offset:896
	global_load_dwordx4 v[148:151], v186, s[70:71] offset:896
	global_load_dwordx4 v[88:91], v186, s[66:67] offset:960
	global_load_dwordx4 v[152:155], v186, s[70:71] offset:960
	v_mov_b64_e32 v[24:25], 0
	v_mov_b64_e32 v[26:27], 0
	s_waitcnt vmcnt(30)
	v_mfma_f32_16x16x32_bf16 v[24:27], v[92:95], v[28:31], v[24:27]
	global_load_dwordx4 v[28:31], v186, s[66:67] offset:1024
	global_load_dwordx4 v[92:95], v186, s[70:71] offset:1024
	s_waitcnt vmcnt(30)
	v_mfma_f32_16x16x32_bf16 v[24:27], v[96:99], v[32:35], v[24:27]
	global_load_dwordx4 v[32:35], v186, s[66:67] offset:1088
	global_load_dwordx4 v[96:99], v186, s[70:71] offset:1088
	s_waitcnt vmcnt(30)
	v_mfma_f32_16x16x32_bf16 v[24:27], v[100:103], v[36:39], v[24:27]
	global_load_dwordx4 v[36:39], v186, s[66:67] offset:1152
	global_load_dwordx4 v[100:103], v186, s[70:71] offset:1152
	s_waitcnt vmcnt(30)
	v_mfma_f32_16x16x32_bf16 v[24:27], v[104:107], v[40:43], v[24:27]
	global_load_dwordx4 v[40:43], v186, s[66:67] offset:1216
	global_load_dwordx4 v[104:107], v186, s[70:71] offset:1216
	s_waitcnt vmcnt(30)
	v_mfma_f32_16x16x32_bf16 v[24:27], v[108:111], v[44:47], v[24:27]
	global_load_dwordx4 v[44:47], v186, s[66:67] offset:1280
	global_load_dwordx4 v[108:111], v186, s[70:71] offset:1280
	s_waitcnt vmcnt(30)
	v_mfma_f32_16x16x32_bf16 v[24:27], v[112:115], v[48:51], v[24:27]
	global_load_dwordx4 v[48:51], v186, s[66:67] offset:1344
	global_load_dwordx4 v[112:115], v186, s[70:71] offset:1344
	s_waitcnt vmcnt(30)
	v_mfma_f32_16x16x32_bf16 v[24:27], v[116:119], v[52:55], v[24:27]
	global_load_dwordx4 v[52:55], v186, s[66:67] offset:1408
	global_load_dwordx4 v[116:119], v186, s[70:71] offset:1408
	s_waitcnt vmcnt(30)
	v_mfma_f32_16x16x32_bf16 v[24:27], v[120:123], v[56:59], v[24:27]
	global_load_dwordx4 v[56:59], v186, s[66:67] offset:1472
	global_load_dwordx4 v[120:123], v186, s[70:71] offset:1472
	s_waitcnt vmcnt(30)
	v_mfma_f32_16x16x32_bf16 v[24:27], v[124:127], v[60:63], v[24:27]
	global_load_dwordx4 v[60:63], v186, s[66:67] offset:1536
	global_load_dwordx4 v[124:127], v186, s[70:71] offset:1536
	s_waitcnt vmcnt(30)
	v_mfma_f32_16x16x32_bf16 v[24:27], v[128:131], v[64:67], v[24:27]
	global_load_dwordx4 v[64:67], v186, s[66:67] offset:1600
	global_load_dwordx4 v[128:131], v186, s[70:71] offset:1600
	s_waitcnt vmcnt(30)
	v_mfma_f32_16x16x32_bf16 v[24:27], v[132:135], v[68:71], v[24:27]
	global_load_dwordx4 v[68:71], v186, s[66:67] offset:1664
	global_load_dwordx4 v[132:135], v186, s[70:71] offset:1664
	s_waitcnt vmcnt(30)
	v_mfma_f32_16x16x32_bf16 v[24:27], v[136:139], v[72:75], v[24:27]
	global_load_dwordx4 v[72:75], v186, s[66:67] offset:1728
	global_load_dwordx4 v[136:139], v186, s[70:71] offset:1728
	s_waitcnt vmcnt(30)
; DI unsigned pk2(float lo, float hi) { const f32x2 v = {lo, hi}; return __builtin_bit_cast(unsigned, __builtin_convertvector(v, bf2_t)); }
; DI void gemm_ple(const Params& p, int bid, int nb, char* smem, const int tid) {
;     ...
;                     for (int e = 0; e < 4; ++e) g[e] = __builtin_amdgcn_rcpf(1.0f + __builtin_amdgcn_exp2f(-LOG2E * gate[i][j][e]));
;                     gpk[i][j].x = pk2(g[0], g[1]); gpk[i][j].y = pk2(g[2], g[3]);
;                 }
;         }
;         f32x4 acc[4][4]; zero_acc(acc);
;         gemm_stream2(PB, 256, WP, 256, 256, m0, n0, have, XN, 1024, WG, 1024, tm2 * 256, tn2 * 128, smem, acc, tid, rg);
; #pragma unroll
;         for (int i = 0; i < 4; ++i)
; #pragma unroll
;             for (int j = 0; j < 4; ++j) {
;                 acc[i][j][0] *= __uint_as_float(gpk[i][j].x << 16); acc[i][j][1] *= __uint_as_float(gpk[i][j].x & 0xffff0000u);
;                 acc[i][j][2] *= __uint_as_float(gpk[i][j].y << 16); acc[i][j][3] *= __uint_as_float(gpk[i][j].y & 0xffff0000u);
;             }
;         if (m0 < NP) epi_y<0>(p, acc, m0, n0, tid); else epi_y<1>(p, acc, m0, n0, tid);
	v_mfma_f32_16x16x32_bf16 v[24:27], v[140:143], v[76:79], v[24:27]
	global_load_dwordx4 v[76:79], v186, s[66:67] offset:1792
	global_load_dwordx4 v[140:143], v186, s[70:71] offset:1792
	s_waitcnt vmcnt(30)
	v_mfma_f32_16x16x32_bf16 v[24:27], v[144:147], v[80:83], v[24:27]
	global_load_dwordx4 v[80:83], v186, s[66:67] offset:1856
	global_load_dwordx4 v[144:147], v186, s[70:71] offset:1856
	s_waitcnt vmcnt(30)
	v_mfma_f32_16x16x32_bf16 v[24:27], v[148:151], v[84:87], v[24:27]
	global_load_dwordx4 v[84:87], v186, s[66:67] offset:1920
	global_load_dwordx4 v[148:151], v186, s[70:71] offset:1920
	s_waitcnt vmcnt(30)
	v_mfma_f32_16x16x32_bf16 v[24:27], v[152:155], v[88:91], v[24:27]
	global_load_dwordx4 v[88:91], v186, s[66:67] offset:1984
	global_load_dwordx4 v[152:155], v186, s[70:71] offset:1984
	s_waitcnt vmcnt(30)
	v_mfma_f32_16x16x32_bf16 v[24:27], v[92:95], v[28:31], v[24:27]
	s_waitcnt vmcnt(28)
	v_mfma_f32_16x16x32_bf16 v[24:27], v[96:99], v[32:35], v[24:27]
	s_waitcnt vmcnt(26)
	v_mfma_f32_16x16x32_bf16 v[24:27], v[100:103], v[36:39], v[24:27]
	s_waitcnt vmcnt(24)
	v_mfma_f32_16x16x32_bf16 v[24:27], v[104:107], v[40:43], v[24:27]
	s_waitcnt vmcnt(22)
	v_mfma_f32_16x16x32_bf16 v[24:27], v[108:111], v[44:47], v[24:27]
	s_waitcnt vmcnt(20)
	v_mfma_f32_16x16x32_bf16 v[24:27], v[112:115], v[48:51], v[24:27]
	s_waitcnt vmcnt(18)
	v_mfma_f32_16x16x32_bf16 v[24:27], v[116:119], v[52:55], v[24:27]
	s_waitcnt vmcnt(16)
	v_mfma_f32_16x16x32_bf16 v[24:27], v[120:123], v[56:59], v[24:27]
	s_waitcnt vmcnt(14)
	v_mfma_f32_16x16x32_bf16 v[24:27], v[124:127], v[60:63], v[24:27]
	s_waitcnt vmcnt(12)
	v_mfma_f32_16x16x32_bf16 v[24:27], v[128:131], v[64:67], v[24:27]
	s_waitcnt vmcnt(10)
	v_mfma_f32_16x16x32_bf16 v[24:27], v[132:135], v[68:71], v[24:27]
	s_waitcnt vmcnt(8)
	v_mfma_f32_16x16x32_bf16 v[24:27], v[136:139], v[72:75], v[24:27]
	s_waitcnt vmcnt(6)
	v_mfma_f32_16x16x32_bf16 v[24:27], v[140:143], v[76:79], v[24:27]
	s_waitcnt vmcnt(4)
	v_mfma_f32_16x16x32_bf16 v[24:27], v[144:147], v[80:83], v[24:27]
	s_waitcnt vmcnt(2)
	v_mfma_f32_16x16x32_bf16 v[24:27], v[148:151], v[84:87], v[24:27]
	s_waitcnt vmcnt(0)
	v_mfma_f32_16x16x32_bf16 v[24:27], v[152:155], v[88:91], v[24:27]
	s_nop 7
	s_nop 7
	v_mul_f32_e32 v28, 0xbfb8aa3b, v24
	v_mul_f32_e32 v29, 0xbfb8aa3b, v25
	v_mul_f32_e32 v30, 0xbfb8aa3b, v26
	v_mul_f32_e32 v31, 0xbfb8aa3b, v27
	v_exp_f32_e32 v28, v28
	v_exp_f32_e32 v29, v29
	v_exp_f32_e32 v30, v30
	v_exp_f32_e32 v31, v31
	s_nop 0
	v_add_f32_e32 v28, 1.0, v28
	v_add_f32_e32 v29, 1.0, v29
	v_add_f32_e32 v30, 1.0, v30
	v_add_f32_e32 v31, 1.0, v31
	v_rcp_f32_e32 v28, v28
	v_rcp_f32_e32 v29, v29
	v_rcp_f32_e32 v30, v30
	v_rcp_f32_e32 v31, v31
	s_nop 0
	v_cvt_pk_bf16_f32 v28, v28, v29
	v_cvt_pk_bf16_f32 v29, v30, v31
	ds_write_b64 v187, v[28:29]
	s_waitcnt lgkmcnt(0)
	s_barrier
	s_branch .Lpss_next
.Lpss_proj:
	v_lshl_add_u32 v186, v191, 9, v189
	s_lshl_b32 s1, s93, 13
	s_add_u32 s1, s1, 0x3220000
	s_add_u32 s66, s88, s1
	s_addc_u32 s67, s89, 0
	s_lshl_b32 s1, s3, 9
	s_add_u32 s1, s1, 0x29a0000
	s_add_u32 s70, s88, s1
	s_addc_u32 s71, s89, 0
	global_load_dwordx4 v[28:31], v186, s[66:67] offset:0
	global_load_dwordx4 v[92:95], v186, s[70:71] offset:0
	global_load_dwordx4 v[32:35], v186, s[66:67] offset:64
	global_load_dwordx4 v[96:99], v186, s[70:71] offset:64
	global_load_dwordx4 v[36:39], v186, s[66:67] offset:128
	global_load_dwordx4 v[100:103], v186, s[70:71] offset:128
	global_load_dwordx4 v[40:43], v186, s[66:67] offset:192
	global_load_dwordx4 v[104:107], v186, s[70:71] offset:192
	global_load_dwordx4 v[44:47], v186, s[66:67] offset:256
	global_load_dwordx4 v[108:111], v186, s[70:71] offset:256
	global_load_dwordx4 v[48:51], v186, s[66:67] offset:320
	global_load_dwordx4 v[112:115], v186, s[70:71] offset:320
	global_load_dwordx4 v[52:55], v186, s[66:67] offset:384
	global_load_dwordx4 v[116:119], v186, s[70:71] offset:384
	global_load_dwordx4 v[56:59], v186, s[66:67] offset:448
	global_load_dwordx4 v[120:123], v186, s[70:71] offset:448
	v_mov_b64_e32 v[24:25], 0
	v_mov_b64_e32 v[26:27], 0
	s_waitcnt vmcnt(14)
	v_mfma_f32_16x16x32_bf16 v[24:27], v[92:95], v[28:31], v[24:27]
	s_waitcnt vmcnt(12)
	v_mfma_f32_16x16x32_bf16 v[24:27], v[96:99], v[32:35], v[24:27]
	s_waitcnt vmcnt(10)
	v_mfma_f32_16x16x32_bf16 v[24:27], v[100:103], v[36:39], v[24:27]
	s_waitcnt vmcnt(8)
	v_mfma_f32_16x16x32_bf16 v[24:27], v[104:107], v[40:43], v[24:27]
	s_waitcnt vmcnt(6)
	v_mfma_f32_16x16x32_bf16 v[24:27], v[108:111], v[44:47], v[24:27]
	s_waitcnt vmcnt(4)
	v_mfma_f32_16x16x32_bf16 v[24:27], v[112:115], v[48:51], v[24:27]
	s_waitcnt vmcnt(2)
	v_mfma_f32_16x16x32_bf16 v[24:27], v[116:119], v[52:55], v[24:27]
	s_waitcnt vmcnt(0)
	v_mfma_f32_16x16x32_bf16 v[24:27], v[120:123], v[56:59], v[24:27]
	s_lshl_b32 s1, s93, 16
	s_lshl_b32 s2, s3, 2
	s_add_u32 s1, s1, s2
	s_add_u32 s1, s1, 0x12595000
	s_add_u32 s74, s88, s1
	s_addc_u32 s75, s89, 0
	v_lshl_add_u32 v188, v191, 12, v189
	s_barrier
	ds_read_b64 v[28:29], v187
	s_waitcnt lgkmcnt(0)
	v_lshlrev_b32_e32 v30, 16, v28
	v_and_b32_e32 v31, 0xffff0000, v28
	v_lshlrev_b32_e32 v32, 16, v29
	v_and_b32_e32 v33, 0xffff0000, v29
	s_nop 7
	s_nop 7
	v_mul_f32_e32 v24, v24, v30
	v_mul_f32_e32 v25, v25, v31
	v_mul_f32_e32 v26, v26, v32
	v_mul_f32_e32 v27, v27, v33
	global_store_dwordx4 v188, v[24:27], s[74:75]
.Lpss_next:
	s_add_u32 s55, s55, s53
	s_cmpk_lt_u32 s55, 0x100
	s_cbranch_scc0 .Lple_exit
	s_barrier
	s_branch .Lpss_u
